# S step with both groups active: the second group's K fragments are requested during the first group's PV MFMAs as its fragment registers free up
# speedup vs baseline: 1.0088x; 1.0088x over previous
.Lsb16_done_a_0:
	s_cmp_eq_u32 s56, 0
	s_cbranch_scc1 .Lsb16_g1only_0
	s_cmp_eq_u32 s57, 0
	s_cbranch_scc1 .Lsb16_g0only_0
	v_subrev_u32_e32 v146, s94, v236
	v_lshrrev_b32_e64 v146, v146, s77
	v_and_b32_e32 v146, 1, v146
	v_cmp_ne_u32_e32 vcc, 0, v146
	s_nop 1
	v_cndmask_b32_e32 v146, v213, v100, vcc
	s_waitcnt lgkmcnt(9)
	v_mfma_f32_16x16x32_bf16 v[34:37], v[50:53], v[66:69], 0
	s_waitcnt lgkmcnt(8)
	v_mfma_f32_16x16x32_bf16 v[34:37], v[54:57], v[70:73], v[34:37]
	ds_read_b128 v[50:53], v234 offset:6912
	ds_read_b128 v[54:57], v234 offset:6976
	s_waitcnt lgkmcnt(9)
	v_mfma_f32_16x16x32_bf16 v[38:41], v[58:61], v[66:69], 0
	s_waitcnt lgkmcnt(8)
	v_mfma_f32_16x16x32_bf16 v[38:41], v[62:65], v[70:73], v[38:41]
	ds_read_b128 v[58:61], v234 offset:9216
	ds_read_b128 v[62:65], v234 offset:9280
	s_waitcnt lgkmcnt(9)
	v_mfma_f32_16x16x32_bf16 v[42:45], v[138:141], v[66:69], 0
	s_waitcnt lgkmcnt(8)
	v_mfma_f32_16x16x32_bf16 v[42:45], v[142:145], v[70:73], v[42:45]
	s_waitcnt lgkmcnt(3)
	v_mfma_f32_16x16x32_bf16 v[46:49], v[50:53], v[66:69], 0
	s_waitcnt lgkmcnt(2)
	v_mfma_f32_16x16x32_bf16 v[46:49], v[54:57], v[70:73], v[46:49]
	ds_read_b128 v[50:53], v234 offset:11520
	ds_read_b128 v[54:57], v234 offset:11584
	v_fma_f32 v34, v34, s48, v146
	v_fma_f32 v35, v35, s48, v146
	v_fma_f32 v36, v36, s48, v146
	v_fma_f32 v37, v37, s48, v146
	v_fma_f32 v38, v38, s48, v146
	v_fma_f32 v39, v39, s48, v146
	v_fma_f32 v40, v40, s48, v146
	v_fma_f32 v41, v41, s48, v146
	v_fma_f32 v42, v42, s48, v146
	v_fma_f32 v43, v43, s48, v146
	v_fma_f32 v44, v44, s48, v146
	v_fma_f32 v45, v45, s48, v146
	v_fma_f32 v46, v46, s48, v146
	v_fma_f32 v47, v47, s48, v146
	v_fma_f32 v48, v48, s48, v146
	v_fma_f32 v49, v49, s48, v146
	s_cmp_lg_u32 s76, s72
	s_cbranch_scc1 .Lsb16_nm0_0a
	s_lshl_b32 s83, s76, 6
	v_subrev_u32_e32 v146, s83, v239
	v_cmp_le_i32_e64 s[28:29], 0, v146
	s_nop 1
	v_cndmask_b32_e64 v34, v213, v34, s[28:29]
	v_cmp_le_i32_e64 s[28:29], 1, v146
	s_nop 1
	v_cndmask_b32_e64 v35, v213, v35, s[28:29]
	v_cmp_le_i32_e64 s[28:29], 2, v146
	s_nop 1
	v_cndmask_b32_e64 v36, v213, v36, s[28:29]
	v_cmp_le_i32_e64 s[28:29], 3, v146
	s_nop 1
	v_cndmask_b32_e64 v37, v213, v37, s[28:29]
	v_cmp_le_i32_e64 s[28:29], 16, v146
	s_nop 1
	v_cndmask_b32_e64 v38, v213, v38, s[28:29]
	v_cmp_le_i32_e64 s[28:29], 17, v146
	s_nop 1
	v_cndmask_b32_e64 v39, v213, v39, s[28:29]
	v_cmp_le_i32_e64 s[28:29], 18, v146
	s_nop 1
	v_cndmask_b32_e64 v40, v213, v40, s[28:29]
	v_cmp_le_i32_e64 s[28:29], 19, v146
	s_nop 1
	v_cndmask_b32_e64 v41, v213, v41, s[28:29]
	v_cmp_le_i32_e64 s[28:29], 32, v146
	s_nop 1
	v_cndmask_b32_e64 v42, v213, v42, s[28:29]
	v_cmp_le_i32_e64 s[28:29], 33, v146
	s_nop 1
	v_cndmask_b32_e64 v43, v213, v43, s[28:29]
	v_cmp_le_i32_e64 s[28:29], 34, v146
	s_nop 1
	v_cndmask_b32_e64 v44, v213, v44, s[28:29]
	v_cmp_le_i32_e64 s[28:29], 35, v146
	s_nop 1
	v_cndmask_b32_e64 v45, v213, v45, s[28:29]
	v_cmp_le_i32_e64 s[28:29], 48, v146
	s_nop 1
	v_cndmask_b32_e64 v46, v213, v46, s[28:29]
	v_cmp_le_i32_e64 s[28:29], 49, v146
	s_nop 1
	v_cndmask_b32_e64 v47, v213, v47, s[28:29]
	v_cmp_le_i32_e64 s[28:29], 50, v146
	s_nop 1
	v_cndmask_b32_e64 v48, v213, v48, s[28:29]
	v_cmp_le_i32_e64 s[28:29], 51, v146
	s_nop 1
	v_cndmask_b32_e64 v49, v213, v49, s[28:29]
.Lsb16_nm0_0a:
	v_exp_f32_e32 v34, v34
	v_exp_f32_e32 v35, v35
	v_exp_f32_e32 v36, v36
	v_exp_f32_e32 v37, v37
	v_exp_f32_e32 v38, v38
	v_exp_f32_e32 v39, v39
	v_exp_f32_e32 v40, v40
	v_exp_f32_e32 v41, v41
	v_exp_f32_e32 v42, v42
	v_exp_f32_e32 v43, v43
	v_exp_f32_e32 v44, v44
	v_exp_f32_e32 v45, v45
	v_exp_f32_e32 v46, v46
	v_exp_f32_e32 v47, v47
	v_exp_f32_e32 v48, v48
	v_exp_f32_e32 v49, v49
	v_add_f32_e32 v138, v34, v35
	v_add_f32_e32 v139, v36, v37
	v_add_f32_e32 v140, v38, v39
	v_add_f32_e32 v141, v40, v41
	v_add_f32_e32 v138, v138, v42
	v_add_f32_e32 v139, v139, v43
	v_add_f32_e32 v140, v140, v44
	v_add_f32_e32 v141, v141, v45
	v_add_f32_e32 v138, v138, v46
	v_add_f32_e32 v139, v139, v47
	v_add_f32_e32 v140, v140, v48
	v_add_f32_e32 v141, v141, v49
	v_add_f32_e32 v138, v138, v139
	v_add_f32_e32 v140, v140, v141
	v_add_f32_e32 v138, v138, v140
	v_add_f32_e32 v129, v129, v138
	v_cvt_pk_bf16_f32 v138, v34, v35
	v_cvt_pk_bf16_f32 v139, v36, v37
	v_cvt_pk_bf16_f32 v140, v38, v39
	v_cvt_pk_bf16_f32 v141, v40, v41
	v_cvt_pk_bf16_f32 v142, v42, v43
	v_cvt_pk_bf16_f32 v143, v44, v45
	v_cvt_pk_bf16_f32 v144, v46, v47
	v_cvt_pk_bf16_f32 v145, v48, v49
	ds_read_b128 v[34:37], v234 offset:13824
	ds_read_b128 v[38:41], v234 offset:13888
	ds_read_b128 v[42:45], v234 offset:16128
	ds_read_b128 v[46:49], v234 offset:16192
	s_waitcnt lgkmcnt(7)
	v_mfma_f32_16x16x32_bf16 v[2:5], v[58:61], v[138:141], v[2:5]
	s_waitcnt lgkmcnt(6)
	v_mfma_f32_16x16x32_bf16 v[2:5], v[62:65], v[142:145], v[2:5]
	ds_read_b128 v[58:61], v234 offset:2304
	ds_read_b128 v[62:65], v234 offset:2368
	s_waitcnt lgkmcnt(7)
	v_mfma_f32_16x16x32_bf16 v[6:9], v[50:53], v[138:141], v[6:9]
	s_waitcnt lgkmcnt(6)
	v_mfma_f32_16x16x32_bf16 v[6:9], v[54:57], v[142:145], v[6:9]
	ds_read_b128 v[50:53], v234
	ds_read_b128 v[54:57], v234 offset:64
	s_waitcnt lgkmcnt(7)
	v_mfma_f32_16x16x32_bf16 v[10:13], v[34:37], v[138:141], v[10:13]
	s_waitcnt lgkmcnt(6)
	v_mfma_f32_16x16x32_bf16 v[10:13], v[38:41], v[142:145], v[10:13]
	s_waitcnt lgkmcnt(5)
	v_mfma_f32_16x16x32_bf16 v[14:17], v[42:45], v[138:141], v[14:17]
	s_waitcnt lgkmcnt(4)
	v_mfma_f32_16x16x32_bf16 v[14:17], v[46:49], v[142:145], v[14:17]
	ds_read_b128 v[138:141], v234 offset:4608
	ds_read_b128 v[142:145], v234 offset:4672
	v_subrev_u32_e32 v146, s94, v236
	v_add_u32_e32 v146, 2, v146
	v_lshrrev_b32_e64 v146, v146, s77
	v_and_b32_e32 v146, 1, v146
	v_cmp_ne_u32_e32 vcc, 0, v146
	s_nop 1
	v_cndmask_b32_e32 v146, v213, v100, vcc
	s_waitcnt lgkmcnt(3)
	v_mfma_f32_16x16x32_bf16 v[34:37], v[50:53], v[74:77], 0
	s_waitcnt lgkmcnt(2)
	v_mfma_f32_16x16x32_bf16 v[34:37], v[54:57], v[78:81], v[34:37]
	ds_read_b128 v[50:53], v234 offset:6912
	ds_read_b128 v[54:57], v234 offset:6976
	s_waitcnt lgkmcnt(5)
	v_mfma_f32_16x16x32_bf16 v[38:41], v[58:61], v[74:77], 0
	s_waitcnt lgkmcnt(4)
	v_mfma_f32_16x16x32_bf16 v[38:41], v[62:65], v[78:81], v[38:41]
	ds_read_b128 v[58:61], v234 offset:9216
	ds_read_b128 v[62:65], v234 offset:9280
	s_waitcnt lgkmcnt(5)
	v_mfma_f32_16x16x32_bf16 v[42:45], v[138:141], v[74:77], 0
	s_waitcnt lgkmcnt(4)
	v_mfma_f32_16x16x32_bf16 v[42:45], v[142:145], v[78:81], v[42:45]
	s_waitcnt lgkmcnt(3)
	v_mfma_f32_16x16x32_bf16 v[46:49], v[50:53], v[74:77], 0
	s_waitcnt lgkmcnt(2)
	v_mfma_f32_16x16x32_bf16 v[46:49], v[54:57], v[78:81], v[46:49]
	ds_read_b128 v[50:53], v234 offset:11520
	ds_read_b128 v[54:57], v234 offset:11584
	v_fma_f32 v34, v34, s48, v146
	v_fma_f32 v35, v35, s48, v146
	v_fma_f32 v36, v36, s48, v146
	v_fma_f32 v37, v37, s48, v146
	v_fma_f32 v38, v38, s48, v146
	v_fma_f32 v39, v39, s48, v146
	v_fma_f32 v40, v40, s48, v146
	v_fma_f32 v41, v41, s48, v146
	v_fma_f32 v42, v42, s48, v146
	v_fma_f32 v43, v43, s48, v146
	v_fma_f32 v44, v44, s48, v146
	v_fma_f32 v45, v45, s48, v146
	v_fma_f32 v46, v46, s48, v146
	v_fma_f32 v47, v47, s48, v146
	v_fma_f32 v48, v48, s48, v146
	v_fma_f32 v49, v49, s48, v146
	s_cmp_lg_u32 s76, s72
	s_cbranch_scc1 .Lsb16_nm1_0b
	s_lshl_b32 s83, s76, 6
	v_subrev_u32_e32 v146, s83, v239
	v_add_u32_e32 v146, 2, v146
	v_cmp_le_i32_e64 s[28:29], 0, v146
	s_nop 1
	v_cndmask_b32_e64 v34, v213, v34, s[28:29]
	v_cmp_le_i32_e64 s[28:29], 1, v146
	s_nop 1
	v_cndmask_b32_e64 v35, v213, v35, s[28:29]
	v_cmp_le_i32_e64 s[28:29], 2, v146
	s_nop 1
	v_cndmask_b32_e64 v36, v213, v36, s[28:29]
	v_cmp_le_i32_e64 s[28:29], 3, v146
	s_nop 1
	v_cndmask_b32_e64 v37, v213, v37, s[28:29]
	v_cmp_le_i32_e64 s[28:29], 16, v146
	s_nop 1
	v_cndmask_b32_e64 v38, v213, v38, s[28:29]
	v_cmp_le_i32_e64 s[28:29], 17, v146
	s_nop 1
	v_cndmask_b32_e64 v39, v213, v39, s[28:29]
	v_cmp_le_i32_e64 s[28:29], 18, v146
	s_nop 1
	v_cndmask_b32_e64 v40, v213, v40, s[28:29]
	v_cmp_le_i32_e64 s[28:29], 19, v146
	s_nop 1
	v_cndmask_b32_e64 v41, v213, v41, s[28:29]
	v_cmp_le_i32_e64 s[28:29], 32, v146
	s_nop 1
	v_cndmask_b32_e64 v42, v213, v42, s[28:29]
	v_cmp_le_i32_e64 s[28:29], 33, v146
	s_nop 1
	v_cndmask_b32_e64 v43, v213, v43, s[28:29]
	v_cmp_le_i32_e64 s[28:29], 34, v146
	s_nop 1
	v_cndmask_b32_e64 v44, v213, v44, s[28:29]
	v_cmp_le_i32_e64 s[28:29], 35, v146
	s_nop 1
	v_cndmask_b32_e64 v45, v213, v45, s[28:29]
	v_cmp_le_i32_e64 s[28:29], 48, v146
	s_nop 1
	v_cndmask_b32_e64 v46, v213, v46, s[28:29]
	v_cmp_le_i32_e64 s[28:29], 49, v146
	s_nop 1
	v_cndmask_b32_e64 v47, v213, v47, s[28:29]
	v_cmp_le_i32_e64 s[28:29], 50, v146
	s_nop 1
	v_cndmask_b32_e64 v48, v213, v48, s[28:29]
	v_cmp_le_i32_e64 s[28:29], 51, v146
	s_nop 1
	v_cndmask_b32_e64 v49, v213, v49, s[28:29]

.Lsb16_g0only_0:
	v_subrev_u32_e32 v146, s94, v236
	v_lshrrev_b32_e64 v146, v146, s77
	v_and_b32_e32 v146, 1, v146
	v_cmp_ne_u32_e32 vcc, 0, v146
	s_nop 1
	v_cndmask_b32_e32 v146, v213, v100, vcc
	s_waitcnt lgkmcnt(9)
	v_mfma_f32_16x16x32_bf16 v[34:37], v[50:53], v[66:69], 0
	s_waitcnt lgkmcnt(8)
	v_mfma_f32_16x16x32_bf16 v[34:37], v[54:57], v[70:73], v[34:37]
	ds_read_b128 v[50:53], v234 offset:6912
	ds_read_b128 v[54:57], v234 offset:6976
	s_waitcnt lgkmcnt(9)
	v_mfma_f32_16x16x32_bf16 v[38:41], v[58:61], v[66:69], 0
	s_waitcnt lgkmcnt(8)
	v_mfma_f32_16x16x32_bf16 v[38:41], v[62:65], v[70:73], v[38:41]
	ds_read_b128 v[58:61], v234 offset:9216
	ds_read_b128 v[62:65], v234 offset:9280
	s_waitcnt lgkmcnt(9)
	v_mfma_f32_16x16x32_bf16 v[42:45], v[138:141], v[66:69], 0
	s_waitcnt lgkmcnt(8)
	v_mfma_f32_16x16x32_bf16 v[42:45], v[142:145], v[70:73], v[42:45]
	s_waitcnt lgkmcnt(3)
	v_mfma_f32_16x16x32_bf16 v[46:49], v[50:53], v[66:69], 0
	s_waitcnt lgkmcnt(2)
	v_mfma_f32_16x16x32_bf16 v[46:49], v[54:57], v[70:73], v[46:49]
	ds_read_b128 v[50:53], v234 offset:11520
	ds_read_b128 v[54:57], v234 offset:11584
	v_fma_f32 v34, v34, s48, v146
	v_fma_f32 v35, v35, s48, v146
	v_fma_f32 v36, v36, s48, v146
	v_fma_f32 v37, v37, s48, v146
	v_fma_f32 v38, v38, s48, v146
	v_fma_f32 v39, v39, s48, v146
	v_fma_f32 v40, v40, s48, v146
	v_fma_f32 v41, v41, s48, v146
	v_fma_f32 v42, v42, s48, v146
	v_fma_f32 v43, v43, s48, v146
	v_fma_f32 v44, v44, s48, v146
	v_fma_f32 v45, v45, s48, v146
	v_fma_f32 v46, v46, s48, v146
	v_fma_f32 v47, v47, s48, v146
	v_fma_f32 v48, v48, s48, v146
	v_fma_f32 v49, v49, s48, v146
	s_cmp_lg_u32 s76, s72
	s_cbranch_scc1 .Lsb16_nm0_0d
	s_lshl_b32 s83, s76, 6
	v_subrev_u32_e32 v146, s83, v239
	v_cmp_le_i32_e64 s[28:29], 0, v146
	s_nop 1
	v_cndmask_b32_e64 v34, v213, v34, s[28:29]
	v_cmp_le_i32_e64 s[28:29], 1, v146
	s_nop 1
	v_cndmask_b32_e64 v35, v213, v35, s[28:29]
	v_cmp_le_i32_e64 s[28:29], 2, v146
	s_nop 1
	v_cndmask_b32_e64 v36, v213, v36, s[28:29]
	v_cmp_le_i32_e64 s[28:29], 3, v146
	s_nop 1
	v_cndmask_b32_e64 v37, v213, v37, s[28:29]
	v_cmp_le_i32_e64 s[28:29], 16, v146
	s_nop 1
	v_cndmask_b32_e64 v38, v213, v38, s[28:29]
	v_cmp_le_i32_e64 s[28:29], 17, v146
	s_nop 1
	v_cndmask_b32_e64 v39, v213, v39, s[28:29]
	v_cmp_le_i32_e64 s[28:29], 18, v146
	s_nop 1
	v_cndmask_b32_e64 v40, v213, v40, s[28:29]
	v_cmp_le_i32_e64 s[28:29], 19, v146
	s_nop 1
	v_cndmask_b32_e64 v41, v213, v41, s[28:29]
	v_cmp_le_i32_e64 s[28:29], 32, v146
	s_nop 1
	v_cndmask_b32_e64 v42, v213, v42, s[28:29]
	v_cmp_le_i32_e64 s[28:29], 33, v146
	s_nop 1
	v_cndmask_b32_e64 v43, v213, v43, s[28:29]
	v_cmp_le_i32_e64 s[28:29], 34, v146
	s_nop 1
	v_cndmask_b32_e64 v44, v213, v44, s[28:29]
	v_cmp_le_i32_e64 s[28:29], 35, v146
	s_nop 1
	v_cndmask_b32_e64 v45, v213, v45, s[28:29]
	v_cmp_le_i32_e64 s[28:29], 48, v146
	s_nop 1
	v_cndmask_b32_e64 v46, v213, v46, s[28:29]
	v_cmp_le_i32_e64 s[28:29], 49, v146
	s_nop 1
	v_cndmask_b32_e64 v47, v213, v47, s[28:29]
	v_cmp_le_i32_e64 s[28:29], 50, v146
	s_nop 1
	v_cndmask_b32_e64 v48, v213, v48, s[28:29]
	v_cmp_le_i32_e64 s[28:29], 51, v146
	s_nop 1
	v_cndmask_b32_e64 v49, v213, v49, s[28:29]
.Lsb16_nm0_0d:
	v_exp_f32_e32 v34, v34
	v_exp_f32_e32 v35, v35
	v_exp_f32_e32 v36, v36
	v_exp_f32_e32 v37, v37
	v_exp_f32_e32 v38, v38
	v_exp_f32_e32 v39, v39
	v_exp_f32_e32 v40, v40
	v_exp_f32_e32 v41, v41
	v_exp_f32_e32 v42, v42
	v_exp_f32_e32 v43, v43
	v_exp_f32_e32 v44, v44
	v_exp_f32_e32 v45, v45
	v_exp_f32_e32 v46, v46
	v_exp_f32_e32 v47, v47
	v_exp_f32_e32 v48, v48
	v_exp_f32_e32 v49, v49
	v_add_f32_e32 v138, v34, v35
	v_add_f32_e32 v139, v36, v37
	v_add_f32_e32 v140, v38, v39
	v_add_f32_e32 v141, v40, v41
	v_add_f32_e32 v138, v138, v42
	v_add_f32_e32 v139, v139, v43
	v_add_f32_e32 v140, v140, v44
	v_add_f32_e32 v141, v141, v45
	v_add_f32_e32 v138, v138, v46
	v_add_f32_e32 v139, v139, v47
	v_add_f32_e32 v140, v140, v48
	v_add_f32_e32 v141, v141, v49
	v_add_f32_e32 v138, v138, v139
	v_add_f32_e32 v140, v140, v141
	v_add_f32_e32 v138, v138, v140
	v_add_f32_e32 v129, v129, v138
	v_cvt_pk_bf16_f32 v138, v34, v35
	v_cvt_pk_bf16_f32 v139, v36, v37
	v_cvt_pk_bf16_f32 v140, v38, v39
	v_cvt_pk_bf16_f32 v141, v40, v41
	v_cvt_pk_bf16_f32 v142, v42, v43
	v_cvt_pk_bf16_f32 v143, v44, v45
	v_cvt_pk_bf16_f32 v144, v46, v47
	v_cvt_pk_bf16_f32 v145, v48, v49
	ds_read_b128 v[34:37], v234 offset:13824
	ds_read_b128 v[38:41], v234 offset:13888
	ds_read_b128 v[42:45], v234 offset:16128
	ds_read_b128 v[46:49], v234 offset:16192
	s_waitcnt lgkmcnt(7)
	v_mfma_f32_16x16x32_bf16 v[2:5], v[58:61], v[138:141], v[2:5]
	s_waitcnt lgkmcnt(6)
	v_mfma_f32_16x16x32_bf16 v[2:5], v[62:65], v[142:145], v[2:5]
	s_waitcnt lgkmcnt(5)
	v_mfma_f32_16x16x32_bf16 v[6:9], v[50:53], v[138:141], v[6:9]
	s_waitcnt lgkmcnt(4)
	v_mfma_f32_16x16x32_bf16 v[6:9], v[54:57], v[142:145], v[6:9]
	s_waitcnt lgkmcnt(3)
	v_mfma_f32_16x16x32_bf16 v[10:13], v[34:37], v[138:141], v[10:13]
	s_waitcnt lgkmcnt(2)
	v_mfma_f32_16x16x32_bf16 v[10:13], v[38:41], v[142:145], v[10:13]
	s_waitcnt lgkmcnt(1)
	v_mfma_f32_16x16x32_bf16 v[14:17], v[42:45], v[138:141], v[14:17]
	s_waitcnt lgkmcnt(0)
	v_mfma_f32_16x16x32_bf16 v[14:17], v[46:49], v[142:145], v[14:17]
	s_branch .Lsb16_end_0

.Lsb16_done_a_1:
	s_cmp_eq_u32 s56, 0
	s_cbranch_scc1 .Lsb16_g1only_1
	s_cmp_eq_u32 s57, 0
	s_cbranch_scc1 .Lsb16_g0only_1
	v_subrev_u32_e32 v146, s94, v236
	v_lshrrev_b32_e64 v146, v146, s77
	v_and_b32_e32 v146, 1, v146
	v_cmp_ne_u32_e32 vcc, 0, v146
	s_nop 1
	v_cndmask_b32_e32 v146, v213, v100, vcc
	s_waitcnt lgkmcnt(9)
	v_mfma_f32_16x16x32_bf16 v[34:37], v[50:53], v[66:69], 0
	s_waitcnt lgkmcnt(8)
	v_mfma_f32_16x16x32_bf16 v[34:37], v[54:57], v[70:73], v[34:37]
	ds_read_b128 v[50:53], v234 offset:25344
	ds_read_b128 v[54:57], v234 offset:25408
	s_waitcnt lgkmcnt(9)
	v_mfma_f32_16x16x32_bf16 v[38:41], v[58:61], v[66:69], 0
	s_waitcnt lgkmcnt(8)
	v_mfma_f32_16x16x32_bf16 v[38:41], v[62:65], v[70:73], v[38:41]
	ds_read_b128 v[58:61], v234 offset:27648
	ds_read_b128 v[62:65], v234 offset:27712
	s_waitcnt lgkmcnt(9)
	v_mfma_f32_16x16x32_bf16 v[42:45], v[138:141], v[66:69], 0
	s_waitcnt lgkmcnt(8)
	v_mfma_f32_16x16x32_bf16 v[42:45], v[142:145], v[70:73], v[42:45]
	s_waitcnt lgkmcnt(3)
	v_mfma_f32_16x16x32_bf16 v[46:49], v[50:53], v[66:69], 0
	s_waitcnt lgkmcnt(2)
	v_mfma_f32_16x16x32_bf16 v[46:49], v[54:57], v[70:73], v[46:49]
	ds_read_b128 v[50:53], v234 offset:29952
	ds_read_b128 v[54:57], v234 offset:30016
	v_fma_f32 v34, v34, s48, v146
	v_fma_f32 v35, v35, s48, v146
	v_fma_f32 v36, v36, s48, v146
	v_fma_f32 v37, v37, s48, v146
	v_fma_f32 v38, v38, s48, v146
	v_fma_f32 v39, v39, s48, v146
	v_fma_f32 v40, v40, s48, v146
	v_fma_f32 v41, v41, s48, v146
	v_fma_f32 v42, v42, s48, v146
	v_fma_f32 v43, v43, s48, v146
	v_fma_f32 v44, v44, s48, v146
	v_fma_f32 v45, v45, s48, v146
	v_fma_f32 v46, v46, s48, v146
	v_fma_f32 v47, v47, s48, v146
	v_fma_f32 v48, v48, s48, v146
	v_fma_f32 v49, v49, s48, v146
	s_cmp_lg_u32 s76, s72
	s_cbranch_scc1 .Lsb16_nm0_1a
	s_lshl_b32 s83, s76, 6
	v_subrev_u32_e32 v146, s83, v239
	v_cmp_le_i32_e64 s[28:29], 0, v146
	s_nop 1
	v_cndmask_b32_e64 v34, v213, v34, s[28:29]
	v_cmp_le_i32_e64 s[28:29], 1, v146
	s_nop 1
	v_cndmask_b32_e64 v35, v213, v35, s[28:29]
	v_cmp_le_i32_e64 s[28:29], 2, v146
	s_nop 1
	v_cndmask_b32_e64 v36, v213, v36, s[28:29]
	v_cmp_le_i32_e64 s[28:29], 3, v146
	s_nop 1
	v_cndmask_b32_e64 v37, v213, v37, s[28:29]
	v_cmp_le_i32_e64 s[28:29], 16, v146
	s_nop 1
	v_cndmask_b32_e64 v38, v213, v38, s[28:29]
	v_cmp_le_i32_e64 s[28:29], 17, v146
	s_nop 1
	v_cndmask_b32_e64 v39, v213, v39, s[28:29]
	v_cmp_le_i32_e64 s[28:29], 18, v146
	s_nop 1
	v_cndmask_b32_e64 v40, v213, v40, s[28:29]
	v_cmp_le_i32_e64 s[28:29], 19, v146
	s_nop 1
	v_cndmask_b32_e64 v41, v213, v41, s[28:29]
	v_cmp_le_i32_e64 s[28:29], 32, v146
	s_nop 1
	v_cndmask_b32_e64 v42, v213, v42, s[28:29]
	v_cmp_le_i32_e64 s[28:29], 33, v146
	s_nop 1
	v_cndmask_b32_e64 v43, v213, v43, s[28:29]
	v_cmp_le_i32_e64 s[28:29], 34, v146
	s_nop 1
	v_cndmask_b32_e64 v44, v213, v44, s[28:29]
	v_cmp_le_i32_e64 s[28:29], 35, v146
	s_nop 1
	v_cndmask_b32_e64 v45, v213, v45, s[28:29]
	v_cmp_le_i32_e64 s[28:29], 48, v146
	s_nop 1
	v_cndmask_b32_e64 v46, v213, v46, s[28:29]
	v_cmp_le_i32_e64 s[28:29], 49, v146
	s_nop 1
	v_cndmask_b32_e64 v47, v213, v47, s[28:29]
	v_cmp_le_i32_e64 s[28:29], 50, v146
	s_nop 1
	v_cndmask_b32_e64 v48, v213, v48, s[28:29]
	v_cmp_le_i32_e64 s[28:29], 51, v146
	s_nop 1
	v_cndmask_b32_e64 v49, v213, v49, s[28:29]
.Lsb16_nm0_1a:
	v_exp_f32_e32 v34, v34
	v_exp_f32_e32 v35, v35
	v_exp_f32_e32 v36, v36
	v_exp_f32_e32 v37, v37
	v_exp_f32_e32 v38, v38
	v_exp_f32_e32 v39, v39
	v_exp_f32_e32 v40, v40
	v_exp_f32_e32 v41, v41
	v_exp_f32_e32 v42, v42
	v_exp_f32_e32 v43, v43
	v_exp_f32_e32 v44, v44
	v_exp_f32_e32 v45, v45
	v_exp_f32_e32 v46, v46
	v_exp_f32_e32 v47, v47
	v_exp_f32_e32 v48, v48
	v_exp_f32_e32 v49, v49
	v_add_f32_e32 v138, v34, v35
	v_add_f32_e32 v139, v36, v37
	v_add_f32_e32 v140, v38, v39
	v_add_f32_e32 v141, v40, v41
	v_add_f32_e32 v138, v138, v42
	v_add_f32_e32 v139, v139, v43
	v_add_f32_e32 v140, v140, v44
	v_add_f32_e32 v141, v141, v45
	v_add_f32_e32 v138, v138, v46
	v_add_f32_e32 v139, v139, v47
	v_add_f32_e32 v140, v140, v48
	v_add_f32_e32 v141, v141, v49
	v_add_f32_e32 v138, v138, v139
	v_add_f32_e32 v140, v140, v141
	v_add_f32_e32 v138, v138, v140
	v_add_f32_e32 v129, v129, v138
	v_cvt_pk_bf16_f32 v138, v34, v35
	v_cvt_pk_bf16_f32 v139, v36, v37
	v_cvt_pk_bf16_f32 v140, v38, v39
	v_cvt_pk_bf16_f32 v141, v40, v41
	v_cvt_pk_bf16_f32 v142, v42, v43
	v_cvt_pk_bf16_f32 v143, v44, v45
	v_cvt_pk_bf16_f32 v144, v46, v47
	v_cvt_pk_bf16_f32 v145, v48, v49
	ds_read_b128 v[34:37], v234 offset:32256
	ds_read_b128 v[38:41], v234 offset:32320
	ds_read_b128 v[42:45], v234 offset:34560
	ds_read_b128 v[46:49], v234 offset:34624
	s_waitcnt lgkmcnt(7)
	v_mfma_f32_16x16x32_bf16 v[2:5], v[58:61], v[138:141], v[2:5]
	s_waitcnt lgkmcnt(6)
	v_mfma_f32_16x16x32_bf16 v[2:5], v[62:65], v[142:145], v[2:5]
	ds_read_b128 v[58:61], v234 offset:20736
	ds_read_b128 v[62:65], v234 offset:20800
	s_waitcnt lgkmcnt(7)
	v_mfma_f32_16x16x32_bf16 v[6:9], v[50:53], v[138:141], v[6:9]
	s_waitcnt lgkmcnt(6)
	v_mfma_f32_16x16x32_bf16 v[6:9], v[54:57], v[142:145], v[6:9]
	ds_read_b128 v[50:53], v234 offset:18432
	ds_read_b128 v[54:57], v234 offset:18496
	s_waitcnt lgkmcnt(7)
	v_mfma_f32_16x16x32_bf16 v[10:13], v[34:37], v[138:141], v[10:13]
	s_waitcnt lgkmcnt(6)
	v_mfma_f32_16x16x32_bf16 v[10:13], v[38:41], v[142:145], v[10:13]
	s_waitcnt lgkmcnt(5)
	v_mfma_f32_16x16x32_bf16 v[14:17], v[42:45], v[138:141], v[14:17]
	s_waitcnt lgkmcnt(4)
	v_mfma_f32_16x16x32_bf16 v[14:17], v[46:49], v[142:145], v[14:17]
	ds_read_b128 v[138:141], v234 offset:23040
	ds_read_b128 v[142:145], v234 offset:23104
	v_subrev_u32_e32 v146, s94, v236
	v_add_u32_e32 v146, 2, v146
	v_lshrrev_b32_e64 v146, v146, s77
	v_and_b32_e32 v146, 1, v146
	v_cmp_ne_u32_e32 vcc, 0, v146
	s_nop 1
	v_cndmask_b32_e32 v146, v213, v100, vcc
	s_waitcnt lgkmcnt(3)
	v_mfma_f32_16x16x32_bf16 v[34:37], v[50:53], v[74:77], 0
	s_waitcnt lgkmcnt(2)
	v_mfma_f32_16x16x32_bf16 v[34:37], v[54:57], v[78:81], v[34:37]
	ds_read_b128 v[50:53], v234 offset:25344
	ds_read_b128 v[54:57], v234 offset:25408
	s_waitcnt lgkmcnt(5)
	v_mfma_f32_16x16x32_bf16 v[38:41], v[58:61], v[74:77], 0
	s_waitcnt lgkmcnt(4)
	v_mfma_f32_16x16x32_bf16 v[38:41], v[62:65], v[78:81], v[38:41]
	ds_read_b128 v[58:61], v234 offset:27648
	ds_read_b128 v[62:65], v234 offset:27712
	s_waitcnt lgkmcnt(5)
	v_mfma_f32_16x16x32_bf16 v[42:45], v[138:141], v[74:77], 0
	s_waitcnt lgkmcnt(4)
	v_mfma_f32_16x16x32_bf16 v[42:45], v[142:145], v[78:81], v[42:45]
	s_waitcnt lgkmcnt(3)
	v_mfma_f32_16x16x32_bf16 v[46:49], v[50:53], v[74:77], 0
	s_waitcnt lgkmcnt(2)
	v_mfma_f32_16x16x32_bf16 v[46:49], v[54:57], v[78:81], v[46:49]
	ds_read_b128 v[50:53], v234 offset:29952
	ds_read_b128 v[54:57], v234 offset:30016
	v_fma_f32 v34, v34, s48, v146
	v_fma_f32 v35, v35, s48, v146
	v_fma_f32 v36, v36, s48, v146
	v_fma_f32 v37, v37, s48, v146
	v_fma_f32 v38, v38, s48, v146
	v_fma_f32 v39, v39, s48, v146
	v_fma_f32 v40, v40, s48, v146
	v_fma_f32 v41, v41, s48, v146
	v_fma_f32 v42, v42, s48, v146
	v_fma_f32 v43, v43, s48, v146
	v_fma_f32 v44, v44, s48, v146
	v_fma_f32 v45, v45, s48, v146
	v_fma_f32 v46, v46, s48, v146
	v_fma_f32 v47, v47, s48, v146
	v_fma_f32 v48, v48, s48, v146
	v_fma_f32 v49, v49, s48, v146
	s_cmp_lg_u32 s76, s72
	s_cbranch_scc1 .Lsb16_nm1_1b
	s_lshl_b32 s83, s76, 6
	v_subrev_u32_e32 v146, s83, v239
	v_add_u32_e32 v146, 2, v146
	v_cmp_le_i32_e64 s[28:29], 0, v146
	s_nop 1
	v_cndmask_b32_e64 v34, v213, v34, s[28:29]
	v_cmp_le_i32_e64 s[28:29], 1, v146
	s_nop 1
	v_cndmask_b32_e64 v35, v213, v35, s[28:29]
	v_cmp_le_i32_e64 s[28:29], 2, v146
	s_nop 1
	v_cndmask_b32_e64 v36, v213, v36, s[28:29]
	v_cmp_le_i32_e64 s[28:29], 3, v146
	s_nop 1
	v_cndmask_b32_e64 v37, v213, v37, s[28:29]
	v_cmp_le_i32_e64 s[28:29], 16, v146
	s_nop 1
	v_cndmask_b32_e64 v38, v213, v38, s[28:29]
	v_cmp_le_i32_e64 s[28:29], 17, v146
	s_nop 1
	v_cndmask_b32_e64 v39, v213, v39, s[28:29]
	v_cmp_le_i32_e64 s[28:29], 18, v146
	s_nop 1
	v_cndmask_b32_e64 v40, v213, v40, s[28:29]
	v_cmp_le_i32_e64 s[28:29], 19, v146
	s_nop 1
	v_cndmask_b32_e64 v41, v213, v41, s[28:29]
	v_cmp_le_i32_e64 s[28:29], 32, v146
	s_nop 1
	v_cndmask_b32_e64 v42, v213, v42, s[28:29]
	v_cmp_le_i32_e64 s[28:29], 33, v146
	s_nop 1
	v_cndmask_b32_e64 v43, v213, v43, s[28:29]
	v_cmp_le_i32_e64 s[28:29], 34, v146
	s_nop 1
	v_cndmask_b32_e64 v44, v213, v44, s[28:29]
	v_cmp_le_i32_e64 s[28:29], 35, v146
	s_nop 1
	v_cndmask_b32_e64 v45, v213, v45, s[28:29]
	v_cmp_le_i32_e64 s[28:29], 48, v146
	s_nop 1
	v_cndmask_b32_e64 v46, v213, v46, s[28:29]
	v_cmp_le_i32_e64 s[28:29], 49, v146
	s_nop 1
	v_cndmask_b32_e64 v47, v213, v47, s[28:29]
	v_cmp_le_i32_e64 s[28:29], 50, v146
	s_nop 1
	v_cndmask_b32_e64 v48, v213, v48, s[28:29]
	v_cmp_le_i32_e64 s[28:29], 51, v146
	s_nop 1
	v_cndmask_b32_e64 v49, v213, v49, s[28:29]

.Lsb16_g0only_1:
	v_subrev_u32_e32 v146, s94, v236
	v_lshrrev_b32_e64 v146, v146, s77
	v_and_b32_e32 v146, 1, v146
	v_cmp_ne_u32_e32 vcc, 0, v146
	s_nop 1
	v_cndmask_b32_e32 v146, v213, v100, vcc
	s_waitcnt lgkmcnt(9)
	v_mfma_f32_16x16x32_bf16 v[34:37], v[50:53], v[66:69], 0
	s_waitcnt lgkmcnt(8)
	v_mfma_f32_16x16x32_bf16 v[34:37], v[54:57], v[70:73], v[34:37]
	ds_read_b128 v[50:53], v234 offset:25344
	ds_read_b128 v[54:57], v234 offset:25408
	s_waitcnt lgkmcnt(9)
	v_mfma_f32_16x16x32_bf16 v[38:41], v[58:61], v[66:69], 0
	s_waitcnt lgkmcnt(8)
	v_mfma_f32_16x16x32_bf16 v[38:41], v[62:65], v[70:73], v[38:41]
	ds_read_b128 v[58:61], v234 offset:27648
	ds_read_b128 v[62:65], v234 offset:27712
	s_waitcnt lgkmcnt(9)
	v_mfma_f32_16x16x32_bf16 v[42:45], v[138:141], v[66:69], 0
	s_waitcnt lgkmcnt(8)
	v_mfma_f32_16x16x32_bf16 v[42:45], v[142:145], v[70:73], v[42:45]
	s_waitcnt lgkmcnt(3)
	v_mfma_f32_16x16x32_bf16 v[46:49], v[50:53], v[66:69], 0
	s_waitcnt lgkmcnt(2)
	v_mfma_f32_16x16x32_bf16 v[46:49], v[54:57], v[70:73], v[46:49]
	ds_read_b128 v[50:53], v234 offset:29952
	ds_read_b128 v[54:57], v234 offset:30016
	v_fma_f32 v34, v34, s48, v146
	v_fma_f32 v35, v35, s48, v146
	v_fma_f32 v36, v36, s48, v146
	v_fma_f32 v37, v37, s48, v146
	v_fma_f32 v38, v38, s48, v146
	v_fma_f32 v39, v39, s48, v146
	v_fma_f32 v40, v40, s48, v146
	v_fma_f32 v41, v41, s48, v146
	v_fma_f32 v42, v42, s48, v146
	v_fma_f32 v43, v43, s48, v146
	v_fma_f32 v44, v44, s48, v146
	v_fma_f32 v45, v45, s48, v146
	v_fma_f32 v46, v46, s48, v146
	v_fma_f32 v47, v47, s48, v146
	v_fma_f32 v48, v48, s48, v146
	v_fma_f32 v49, v49, s48, v146
	s_cmp_lg_u32 s76, s72
	s_cbranch_scc1 .Lsb16_nm0_1d
	s_lshl_b32 s83, s76, 6
	v_subrev_u32_e32 v146, s83, v239
	v_cmp_le_i32_e64 s[28:29], 0, v146
	s_nop 1
	v_cndmask_b32_e64 v34, v213, v34, s[28:29]
	v_cmp_le_i32_e64 s[28:29], 1, v146
	s_nop 1
	v_cndmask_b32_e64 v35, v213, v35, s[28:29]
	v_cmp_le_i32_e64 s[28:29], 2, v146
	s_nop 1
	v_cndmask_b32_e64 v36, v213, v36, s[28:29]
	v_cmp_le_i32_e64 s[28:29], 3, v146
	s_nop 1
	v_cndmask_b32_e64 v37, v213, v37, s[28:29]
	v_cmp_le_i32_e64 s[28:29], 16, v146
	s_nop 1
	v_cndmask_b32_e64 v38, v213, v38, s[28:29]
	v_cmp_le_i32_e64 s[28:29], 17, v146
	s_nop 1
	v_cndmask_b32_e64 v39, v213, v39, s[28:29]
	v_cmp_le_i32_e64 s[28:29], 18, v146
	s_nop 1
	v_cndmask_b32_e64 v40, v213, v40, s[28:29]
	v_cmp_le_i32_e64 s[28:29], 19, v146
	s_nop 1
	v_cndmask_b32_e64 v41, v213, v41, s[28:29]
	v_cmp_le_i32_e64 s[28:29], 32, v146
	s_nop 1
	v_cndmask_b32_e64 v42, v213, v42, s[28:29]
	v_cmp_le_i32_e64 s[28:29], 33, v146
	s_nop 1
	v_cndmask_b32_e64 v43, v213, v43, s[28:29]
	v_cmp_le_i32_e64 s[28:29], 34, v146
	s_nop 1
	v_cndmask_b32_e64 v44, v213, v44, s[28:29]
	v_cmp_le_i32_e64 s[28:29], 35, v146
	s_nop 1
	v_cndmask_b32_e64 v45, v213, v45, s[28:29]
	v_cmp_le_i32_e64 s[28:29], 48, v146
	s_nop 1
	v_cndmask_b32_e64 v46, v213, v46, s[28:29]
	v_cmp_le_i32_e64 s[28:29], 49, v146
	s_nop 1
	v_cndmask_b32_e64 v47, v213, v47, s[28:29]
	v_cmp_le_i32_e64 s[28:29], 50, v146
	s_nop 1
	v_cndmask_b32_e64 v48, v213, v48, s[28:29]
	v_cmp_le_i32_e64 s[28:29], 51, v146
	s_nop 1
	v_cndmask_b32_e64 v49, v213, v49, s[28:29]
.Lsb16_nm0_1d:
	v_exp_f32_e32 v34, v34
	v_exp_f32_e32 v35, v35
	v_exp_f32_e32 v36, v36
	v_exp_f32_e32 v37, v37
	v_exp_f32_e32 v38, v38
	v_exp_f32_e32 v39, v39
	v_exp_f32_e32 v40, v40
	v_exp_f32_e32 v41, v41
	v_exp_f32_e32 v42, v42
	v_exp_f32_e32 v43, v43
	v_exp_f32_e32 v44, v44
	v_exp_f32_e32 v45, v45
	v_exp_f32_e32 v46, v46
	v_exp_f32_e32 v47, v47
	v_exp_f32_e32 v48, v48
	v_exp_f32_e32 v49, v49
	v_add_f32_e32 v138, v34, v35
	v_add_f32_e32 v139, v36, v37
	v_add_f32_e32 v140, v38, v39
	v_add_f32_e32 v141, v40, v41
	v_add_f32_e32 v138, v138, v42
	v_add_f32_e32 v139, v139, v43
	v_add_f32_e32 v140, v140, v44
	v_add_f32_e32 v141, v141, v45
	v_add_f32_e32 v138, v138, v46
	v_add_f32_e32 v139, v139, v47
	v_add_f32_e32 v140, v140, v48
	v_add_f32_e32 v141, v141, v49
	v_add_f32_e32 v138, v138, v139
	v_add_f32_e32 v140, v140, v141
	v_add_f32_e32 v138, v138, v140
	v_add_f32_e32 v129, v129, v138
	v_cvt_pk_bf16_f32 v138, v34, v35
	v_cvt_pk_bf16_f32 v139, v36, v37
	v_cvt_pk_bf16_f32 v140, v38, v39
	v_cvt_pk_bf16_f32 v141, v40, v41
	v_cvt_pk_bf16_f32 v142, v42, v43
	v_cvt_pk_bf16_f32 v143, v44, v45
	v_cvt_pk_bf16_f32 v144, v46, v47
	v_cvt_pk_bf16_f32 v145, v48, v49
	ds_read_b128 v[34:37], v234 offset:32256
	ds_read_b128 v[38:41], v234 offset:32320
	ds_read_b128 v[42:45], v234 offset:34560
	ds_read_b128 v[46:49], v234 offset:34624
	s_waitcnt lgkmcnt(7)
	v_mfma_f32_16x16x32_bf16 v[2:5], v[58:61], v[138:141], v[2:5]
	s_waitcnt lgkmcnt(6)
	v_mfma_f32_16x16x32_bf16 v[2:5], v[62:65], v[142:145], v[2:5]
	s_waitcnt lgkmcnt(5)
	v_mfma_f32_16x16x32_bf16 v[6:9], v[50:53], v[138:141], v[6:9]
	s_waitcnt lgkmcnt(4)
	v_mfma_f32_16x16x32_bf16 v[6:9], v[54:57], v[142:145], v[6:9]
	s_waitcnt lgkmcnt(3)
	v_mfma_f32_16x16x32_bf16 v[10:13], v[34:37], v[138:141], v[10:13]
	s_waitcnt lgkmcnt(2)
	v_mfma_f32_16x16x32_bf16 v[10:13], v[38:41], v[142:145], v[10:13]
	s_waitcnt lgkmcnt(1)
	v_mfma_f32_16x16x32_bf16 v[14:17], v[42:45], v[138:141], v[14:17]
	s_waitcnt lgkmcnt(0)
	v_mfma_f32_16x16x32_bf16 v[14:17], v[46:49], v[142:145], v[14:17]
	s_branch .Lsb16_end_1
